# v30 + EpiResid permlane swaps + RMS-scale LDS reads hoisted (one wait instead of eight) in the odd-in and z GEMM epilogues
# speedup vs baseline: 1.0043x; 1.0043x over previous
.LBB0_466:
	s_and_b32 s5, s5, 1
	s_lshl_b32 s5, s5, 10
	v_add_u32_e32 v153, s5, v150
	ds_read_b32 v146, v153
	ds_read_b32 v224, v153 offset:64
	ds_read_b32 v225, v153 offset:128
	ds_read_b32 v226, v153 offset:192
	ds_read_b32 v227, v153 offset:512
	ds_read_b32 v228, v153 offset:576
	ds_read_b32 v229, v153 offset:640
	ds_read_b32 v230, v153 offset:704
	s_cmp_gt_i32 s4, 7
	s_cselect_b64 s[30:31], -1, 0
	s_lshl_b32 s5, s4, 8
	v_lshl_add_u32 v144, s26, 8, v139
	s_add_i32 s26, s5, 0xfffff800
	s_ashr_i32 s27, s26, 31
	s_waitcnt lgkmcnt(0)
	v_mov_b32_e32 v147, v146
	s_cmp_lt_i32 s4, 8
	v_pk_mul_f32 v[128:129], v[128:129], v[146:147] op_sel_hi:[1,0]
	v_pk_mul_f32 v[126:127], v[126:127], v[146:147] op_sel_hi:[1,0]
	s_mov_b64 s[34:35], -1
	v_ashrrev_i32_e32 v145, 31, v144
	v_pk_mul_f32 v[122:123], v[122:123], v[146:147]
	v_lshlrev_b32_e32 v96, 1, v138
	v_pk_mul_f32 v[118:119], v[118:119], v[146:147]
	v_pk_mul_f32 v[114:115], v[114:115], v[146:147]
	s_cbranch_scc1 .LBB0_468
	v_lshlrev_b64 v[158:159], 11, v[144:145]
	v_mov_b32_e32 v147, v146
	v_lshl_add_u64 v[158:159], s[12:13], 0, v[158:159]
	v_pk_mul_f32 v[156:157], v[124:125], v[146:147]
	v_lshl_add_u64 v[158:159], s[26:27], 1, v[158:159]
	s_lshl_b32 s60, s47, 1
	v_cvt_pk_bf16_f32 v154, v122, v123
	v_cvt_pk_bf16_f32 v155, v156, v157
	v_cvt_pk_bf16_f32 v156, v126, v127
	v_cvt_pk_bf16_f32 v157, v128, v129
	v_lshl_add_u64 v[158:159], v[158:159], 0, s[60:61]
	v_lshl_add_u64 v[158:159], v[158:159], 0, v[96:97]
	global_store_dwordx4 v[158:159], v[154:157], off sc1
	s_nop 1
	v_pk_mul_f32 v[156:157], v[120:121], v[146:147]
	v_pk_mul_f32 v[160:161], v[116:117], v[146:147]
	v_cvt_pk_bf16_f32 v154, v118, v119
	v_cvt_pk_bf16_f32 v155, v156, v157
	v_cvt_pk_bf16_f32 v156, v114, v115
	v_lshl_add_u64 v[158:159], v[158:159], 0, s[66:67]
	v_cvt_pk_bf16_f32 v157, v160, v161
	s_mov_b64 s[34:35], 0
	global_store_dwordx4 v[158:159], v[154:157], off sc1
	s_nop 1

.LBB0_470:
	v_mov_b32_e32 v116, v224
	v_or_b32_e32 v114, 16, v144
	v_cndmask_b32_e64 v115, 0, 1, s[30:31]
	s_mov_b64 s[34:35], -1
	v_cmp_ne_u32_e64 s[4:5], 1, v115
	s_waitcnt lgkmcnt(0)
	v_mov_b32_e32 v117, v116
	v_pk_mul_f32 v[112:113], v[112:113], v[116:117] op_sel_hi:[1,0]
	v_pk_mul_f32 v[110:111], v[110:111], v[116:117] op_sel_hi:[1,0]
	s_andn2_b64 vcc, exec, s[30:31]
	v_ashrrev_i32_e32 v115, 31, v114
	v_pk_mul_f32 v[106:107], v[106:107], v[116:117]
	v_pk_mul_f32 v[102:103], v[102:103], v[116:117]
	v_pk_mul_f32 v[98:99], v[98:99], v[116:117]
	s_cbranch_vccnz .LBB0_472
	v_lshlrev_b64 v[122:123], 11, v[114:115]
	v_mov_b32_e32 v117, v116
	v_lshl_add_u64 v[122:123], s[12:13], 0, v[122:123]
	v_pk_mul_f32 v[120:121], v[108:109], v[116:117]
	v_lshl_add_u64 v[122:123], s[26:27], 1, v[122:123]
	s_lshl_b32 s60, s47, 1
	v_cvt_pk_bf16_f32 v118, v106, v107
	v_cvt_pk_bf16_f32 v119, v120, v121
	v_cvt_pk_bf16_f32 v120, v110, v111
	v_cvt_pk_bf16_f32 v121, v112, v113
	v_lshl_add_u64 v[122:123], v[122:123], 0, s[60:61]
	v_lshl_add_u64 v[122:123], v[122:123], 0, v[96:97]
	global_store_dwordx4 v[122:123], v[118:121], off sc1
	s_nop 1
	v_pk_mul_f32 v[120:121], v[104:105], v[116:117]
	v_pk_mul_f32 v[124:125], v[100:101], v[116:117]
	v_cvt_pk_bf16_f32 v118, v102, v103
	v_cvt_pk_bf16_f32 v119, v120, v121
	v_cvt_pk_bf16_f32 v120, v98, v99
	v_lshl_add_u64 v[122:123], v[122:123], 0, s[66:67]
	v_cvt_pk_bf16_f32 v121, v124, v125
	s_mov_b64 s[34:35], 0
	global_store_dwordx4 v[122:123], v[118:121], off sc1
	s_nop 1

.LBB0_474:
	v_mov_b32_e32 v100, v225
	v_or_b32_e32 v98, 32, v144
	s_mov_b64 s[30:31], -1
	s_and_b64 vcc, exec, s[4:5]
	v_ashrrev_i32_e32 v99, 31, v98
	s_waitcnt lgkmcnt(0)
	v_mov_b32_e32 v101, v100
	v_pk_mul_f32 v[94:95], v[94:95], v[100:101] op_sel_hi:[1,0]
	v_pk_mul_f32 v[92:93], v[92:93], v[100:101] op_sel_hi:[1,0]
	v_pk_mul_f32 v[88:89], v[88:89], v[100:101]
	v_pk_mul_f32 v[84:85], v[84:85], v[100:101]
	v_pk_mul_f32 v[80:81], v[80:81], v[100:101]
	s_cbranch_vccnz .LBB0_476
	v_lshlrev_b64 v[106:107], 11, v[98:99]
	v_mov_b32_e32 v101, v100
	v_lshl_add_u64 v[106:107], s[12:13], 0, v[106:107]
	v_pk_mul_f32 v[104:105], v[90:91], v[100:101]
	v_lshl_add_u64 v[106:107], s[26:27], 1, v[106:107]
	s_lshl_b32 s60, s47, 1
	v_cvt_pk_bf16_f32 v102, v88, v89
	v_cvt_pk_bf16_f32 v103, v104, v105
	v_cvt_pk_bf16_f32 v104, v92, v93
	v_cvt_pk_bf16_f32 v105, v94, v95
	v_lshl_add_u64 v[106:107], v[106:107], 0, s[60:61]
	v_lshl_add_u64 v[106:107], v[106:107], 0, v[96:97]
	global_store_dwordx4 v[106:107], v[102:105], off sc1
	s_nop 1
	v_pk_mul_f32 v[104:105], v[86:87], v[100:101]
	v_pk_mul_f32 v[108:109], v[82:83], v[100:101]
	v_cvt_pk_bf16_f32 v102, v84, v85
	v_cvt_pk_bf16_f32 v103, v104, v105
	v_cvt_pk_bf16_f32 v104, v80, v81
	v_lshl_add_u64 v[106:107], v[106:107], 0, s[66:67]
	v_cvt_pk_bf16_f32 v105, v108, v109
	s_mov_b64 s[30:31], 0
	global_store_dwordx4 v[106:107], v[102:105], off sc1
	s_nop 1

.LBB0_478:
	v_mov_b32_e32 v82, v226
	v_or_b32_e32 v80, 48, v144
	s_mov_b64 s[30:31], -1
	s_and_b64 vcc, exec, s[4:5]
	v_ashrrev_i32_e32 v81, 31, v80
	s_waitcnt lgkmcnt(0)
	v_mov_b32_e32 v83, v82
	v_pk_mul_f32 v[78:79], v[78:79], v[82:83] op_sel_hi:[1,0]
	v_pk_mul_f32 v[76:77], v[76:77], v[82:83] op_sel_hi:[1,0]
	v_pk_mul_f32 v[72:73], v[72:73], v[82:83]
	v_pk_mul_f32 v[68:69], v[68:69], v[82:83]
	v_pk_mul_f32 v[64:65], v[64:65], v[82:83]
	s_cbranch_vccnz .LBB0_480
	v_lshlrev_b64 v[88:89], 11, v[80:81]
	v_mov_b32_e32 v83, v82
	v_lshl_add_u64 v[88:89], s[12:13], 0, v[88:89]
	v_pk_mul_f32 v[86:87], v[74:75], v[82:83]
	v_lshl_add_u64 v[88:89], s[26:27], 1, v[88:89]
	s_lshl_b32 s60, s47, 1
	v_cvt_pk_bf16_f32 v84, v72, v73
	v_cvt_pk_bf16_f32 v85, v86, v87
	v_cvt_pk_bf16_f32 v86, v76, v77
	v_cvt_pk_bf16_f32 v87, v78, v79
	v_lshl_add_u64 v[88:89], v[88:89], 0, s[60:61]
	v_lshl_add_u64 v[88:89], v[88:89], 0, v[96:97]
	global_store_dwordx4 v[88:89], v[84:87], off sc1
	s_nop 1
	v_pk_mul_f32 v[86:87], v[70:71], v[82:83]
	v_pk_mul_f32 v[90:91], v[66:67], v[82:83]
	v_cvt_pk_bf16_f32 v84, v68, v69
	v_cvt_pk_bf16_f32 v85, v86, v87
	v_cvt_pk_bf16_f32 v86, v64, v65
	v_lshl_add_u64 v[88:89], v[88:89], 0, s[66:67]
	v_cvt_pk_bf16_f32 v87, v90, v91
	s_mov_b64 s[30:31], 0
	global_store_dwordx4 v[88:89], v[84:87], off sc1
	s_nop 1

.LBB0_482:
	v_mov_b32_e32 v66, v227
	v_add_u32_e32 v64, 0x80, v144
	s_mov_b64 s[30:31], -1
	s_and_b64 vcc, exec, s[4:5]
	v_ashrrev_i32_e32 v65, 31, v64
	s_waitcnt lgkmcnt(0)
	v_mov_b32_e32 v67, v66
	v_pk_mul_f32 v[62:63], v[62:63], v[66:67] op_sel_hi:[1,0]
	v_pk_mul_f32 v[60:61], v[60:61], v[66:67] op_sel_hi:[1,0]
	v_pk_mul_f32 v[56:57], v[56:57], v[66:67]
	v_pk_mul_f32 v[52:53], v[52:53], v[66:67]
	v_pk_mul_f32 v[48:49], v[48:49], v[66:67]
	s_cbranch_vccnz .LBB0_484
	v_lshlrev_b64 v[72:73], 11, v[64:65]
	v_mov_b32_e32 v67, v66
	v_lshl_add_u64 v[72:73], s[12:13], 0, v[72:73]
	v_pk_mul_f32 v[70:71], v[58:59], v[66:67]
	v_lshl_add_u64 v[72:73], s[26:27], 1, v[72:73]
	s_lshl_b32 s60, s47, 1
	v_cvt_pk_bf16_f32 v68, v56, v57
	v_cvt_pk_bf16_f32 v69, v70, v71
	v_cvt_pk_bf16_f32 v70, v60, v61
	v_cvt_pk_bf16_f32 v71, v62, v63
	v_lshl_add_u64 v[72:73], v[72:73], 0, s[60:61]
	v_lshl_add_u64 v[72:73], v[72:73], 0, v[96:97]
	global_store_dwordx4 v[72:73], v[68:71], off sc1
	s_nop 1
	v_pk_mul_f32 v[70:71], v[54:55], v[66:67]
	v_pk_mul_f32 v[74:75], v[50:51], v[66:67]
	v_cvt_pk_bf16_f32 v68, v52, v53
	v_cvt_pk_bf16_f32 v69, v70, v71
	v_cvt_pk_bf16_f32 v70, v48, v49
	v_lshl_add_u64 v[72:73], v[72:73], 0, s[66:67]
	v_cvt_pk_bf16_f32 v71, v74, v75
	s_mov_b64 s[30:31], 0
	global_store_dwordx4 v[72:73], v[68:71], off sc1
	s_nop 1

.LBB0_486:
	v_mov_b32_e32 v50, v228
	v_add_u32_e32 v48, 0x90, v144
	s_mov_b64 s[30:31], -1
	s_and_b64 vcc, exec, s[4:5]
	v_ashrrev_i32_e32 v49, 31, v48
	s_waitcnt lgkmcnt(0)
	v_mov_b32_e32 v51, v50
	v_pk_mul_f32 v[46:47], v[46:47], v[50:51] op_sel_hi:[1,0]
	v_pk_mul_f32 v[44:45], v[44:45], v[50:51] op_sel_hi:[1,0]
	v_pk_mul_f32 v[40:41], v[40:41], v[50:51]
	v_pk_mul_f32 v[36:37], v[36:37], v[50:51]
	v_pk_mul_f32 v[32:33], v[32:33], v[50:51]
	s_cbranch_vccnz .LBB0_488
	v_lshlrev_b64 v[56:57], 11, v[48:49]
	v_mov_b32_e32 v51, v50
	v_lshl_add_u64 v[56:57], s[12:13], 0, v[56:57]
	v_pk_mul_f32 v[54:55], v[42:43], v[50:51]
	v_lshl_add_u64 v[56:57], s[26:27], 1, v[56:57]
	s_lshl_b32 s60, s47, 1
	v_cvt_pk_bf16_f32 v52, v40, v41
	v_cvt_pk_bf16_f32 v53, v54, v55
	v_cvt_pk_bf16_f32 v54, v44, v45
	v_cvt_pk_bf16_f32 v55, v46, v47
	v_lshl_add_u64 v[56:57], v[56:57], 0, s[60:61]
	v_lshl_add_u64 v[56:57], v[56:57], 0, v[96:97]
	global_store_dwordx4 v[56:57], v[52:55], off sc1
	s_nop 1
	v_pk_mul_f32 v[54:55], v[38:39], v[50:51]
	v_pk_mul_f32 v[58:59], v[34:35], v[50:51]
	v_cvt_pk_bf16_f32 v52, v36, v37
	v_cvt_pk_bf16_f32 v53, v54, v55
	v_cvt_pk_bf16_f32 v54, v32, v33
	v_lshl_add_u64 v[56:57], v[56:57], 0, s[66:67]
	v_cvt_pk_bf16_f32 v55, v58, v59
	s_mov_b64 s[30:31], 0
	global_store_dwordx4 v[56:57], v[52:55], off sc1
	s_nop 1

.LBB0_490:
	v_mov_b32_e32 v34, v229
	v_add_u32_e32 v32, 0xa0, v144
	s_mov_b64 s[30:31], -1
	s_and_b64 vcc, exec, s[4:5]
	v_ashrrev_i32_e32 v33, 31, v32
	s_waitcnt lgkmcnt(0)
	v_mov_b32_e32 v35, v34
	v_pk_mul_f32 v[30:31], v[30:31], v[34:35] op_sel_hi:[1,0]
	v_pk_mul_f32 v[28:29], v[28:29], v[34:35] op_sel_hi:[1,0]
	v_pk_mul_f32 v[24:25], v[24:25], v[34:35]
	v_pk_mul_f32 v[20:21], v[20:21], v[34:35]
	v_pk_mul_f32 v[16:17], v[16:17], v[34:35]
	s_cbranch_vccnz .LBB0_492
	v_lshlrev_b64 v[40:41], 11, v[32:33]
	v_mov_b32_e32 v35, v34
	v_lshl_add_u64 v[40:41], s[12:13], 0, v[40:41]
	v_pk_mul_f32 v[38:39], v[26:27], v[34:35]
	v_lshl_add_u64 v[40:41], s[26:27], 1, v[40:41]
	s_lshl_b32 s60, s47, 1
	v_cvt_pk_bf16_f32 v36, v24, v25
	v_cvt_pk_bf16_f32 v37, v38, v39
	v_cvt_pk_bf16_f32 v38, v28, v29
	v_cvt_pk_bf16_f32 v39, v30, v31
	v_lshl_add_u64 v[40:41], v[40:41], 0, s[60:61]
	v_lshl_add_u64 v[40:41], v[40:41], 0, v[96:97]
	global_store_dwordx4 v[40:41], v[36:39], off sc1
	s_nop 1
	v_pk_mul_f32 v[38:39], v[22:23], v[34:35]
	v_pk_mul_f32 v[42:43], v[18:19], v[34:35]
	v_cvt_pk_bf16_f32 v36, v20, v21
	v_cvt_pk_bf16_f32 v37, v38, v39
	v_cvt_pk_bf16_f32 v38, v16, v17
	v_lshl_add_u64 v[40:41], v[40:41], 0, s[66:67]
	v_cvt_pk_bf16_f32 v39, v42, v43
	s_mov_b64 s[30:31], 0
	global_store_dwordx4 v[40:41], v[36:39], off sc1
	s_nop 1

.LBB0_494:
	v_mov_b32_e32 v18, v230
	v_add_u32_e32 v16, 0xb0, v144
	s_mov_b64 s[30:31], -1
	s_and_b64 vcc, exec, s[4:5]
	v_ashrrev_i32_e32 v17, 31, v16
	s_waitcnt lgkmcnt(0)
	v_mov_b32_e32 v19, v18
	v_pk_mul_f32 v[14:15], v[14:15], v[18:19] op_sel_hi:[1,0]
	v_pk_mul_f32 v[12:13], v[12:13], v[18:19] op_sel_hi:[1,0]
	v_pk_mul_f32 v[8:9], v[8:9], v[18:19]
	v_pk_mul_f32 v[4:5], v[4:5], v[18:19]
	v_pk_mul_f32 v[0:1], v[0:1], v[18:19]
	s_cbranch_vccz .LBB0_497
	s_andn2_b64 vcc, exec, s[30:31]
	s_cbranch_vccz .LBB0_498

.LBB0_727:
	s_and_b32 s15, s46, 1
	v_lshl_add_u32 v147, s15, 10, v144
	ds_read_b32 v148, v147
	ds_read_b32 v224, v147 offset:64
	ds_read_b32 v225, v147 offset:128
	ds_read_b32 v226, v147 offset:192
	ds_read_b32 v227, v147 offset:512
	ds_read_b32 v228, v147 offset:576
	ds_read_b32 v229, v147 offset:640
	ds_read_b32 v230, v147 offset:704
	v_lshl_add_u32 v149, s22, 8, v140
	v_lshl_or_b32 v150, s45, 8, v142
	v_ashrrev_i32_e32 v151, 31, v150
	s_andn2_b64 vcc, exec, s[2:3]
	s_waitcnt lgkmcnt(0)
	v_pk_mul_f32 v[128:129], v[128:129], v[148:149] op_sel_hi:[1,0]
	v_pk_mul_f32 v[126:127], v[126:127], v[148:149] op_sel_hi:[1,0]
	v_pk_mul_f32 v[122:123], v[122:123], v[148:149] op_sel_hi:[1,0]
	v_pk_mul_f32 v[124:125], v[124:125], v[148:149] op_sel_hi:[1,0]
	v_cvt_pk_bf16_f32 v126, v126, v127
	v_cvt_pk_bf16_f32 v127, v128, v129
	v_cvt_pk_bf16_f32 v128, v122, v123
	v_mov_b64_e32 v[122:123], s[8:9]
	v_cvt_pk_bf16_f32 v129, v124, v125
	v_mad_i64_i32 v[152:153], s[24:25], v149, s77, v[122:123]
	v_lshlrev_b64 v[124:125], 1, v[150:151]
	v_lshl_add_u64 v[150:151], v[152:153], 0, v[124:125]
	global_store_dwordx4 v[150:151], v[126:129], off sc1
	s_nop 1
	v_pk_mul_f32 v[118:119], v[118:119], v[148:149] op_sel_hi:[1,0]
	v_pk_mul_f32 v[126:127], v[112:113], v[148:149] op_sel_hi:[1,0]
	v_pk_mul_f32 v[112:113], v[110:111], v[148:149] op_sel_hi:[1,0]
	v_pk_mul_f32 v[120:121], v[120:121], v[148:149] op_sel_hi:[1,0]
	v_cvt_pk_bf16_f32 v110, v118, v119
	v_lshl_add_u64 v[118:119], v[150:151], 0, s[66:67]
	v_cvt_pk_bf16_f32 v111, v120, v121
	v_cvt_pk_bf16_f32 v112, v112, v113
	v_cvt_pk_bf16_f32 v113, v126, v127
	s_mov_b64 s[2:3], -1
	global_store_dwordx4 v[118:119], v[110:113], off sc1
	s_nop 1
	v_mov_b32_e32 v110, v224
	v_or_b32_e32 v111, 16, v149
	s_waitcnt lgkmcnt(0)
	v_pk_mul_f32 v[112:113], v[116:117], v[110:111] op_sel_hi:[1,0]
	v_pk_mul_f32 v[114:115], v[114:115], v[110:111] op_sel_hi:[1,0]
	v_pk_mul_f32 v[116:117], v[108:109], v[110:111] op_sel_hi:[1,0]
	v_pk_mul_f32 v[108:109], v[106:107], v[110:111] op_sel_hi:[1,0]
	v_cvt_pk_bf16_f32 v106, v114, v115
	v_cvt_pk_bf16_f32 v107, v112, v113
	v_mad_i64_i32 v[112:113], s[24:25], v111, s77, v[122:123]
	v_cvt_pk_bf16_f32 v108, v108, v109
	v_cvt_pk_bf16_f32 v109, v116, v117
	v_lshl_add_u64 v[112:113], v[112:113], 0, v[124:125]
	global_store_dwordx4 v[112:113], v[106:109], off sc1
	s_nop 1
	v_pk_mul_f32 v[102:103], v[102:103], v[110:111] op_sel_hi:[1,0]
	v_pk_mul_f32 v[106:107], v[94:95], v[110:111] op_sel_hi:[1,0]
	v_pk_mul_f32 v[94:95], v[92:93], v[110:111] op_sel_hi:[1,0]
	v_pk_mul_f32 v[104:105], v[104:105], v[110:111] op_sel_hi:[1,0]
	v_cvt_pk_bf16_f32 v92, v102, v103
	v_lshl_add_u64 v[102:103], v[112:113], 0, s[66:67]
	v_cvt_pk_bf16_f32 v93, v104, v105
	v_cvt_pk_bf16_f32 v94, v94, v95
	v_cvt_pk_bf16_f32 v95, v106, v107
	s_nop 0
	global_store_dwordx4 v[102:103], v[92:95], off sc1
	s_nop 1
	v_mov_b32_e32 v92, v225
	v_or_b32_e32 v93, 32, v149
	s_waitcnt lgkmcnt(0)
	v_pk_mul_f32 v[94:95], v[100:101], v[92:93] op_sel_hi:[1,0]
	v_pk_mul_f32 v[98:99], v[98:99], v[92:93] op_sel_hi:[1,0]
	v_pk_mul_f32 v[100:101], v[90:91], v[92:93] op_sel_hi:[1,0]
	v_pk_mul_f32 v[90:91], v[88:89], v[92:93] op_sel_hi:[1,0]
	v_cvt_pk_bf16_f32 v88, v98, v99
	v_cvt_pk_bf16_f32 v89, v94, v95
	v_mad_i64_i32 v[94:95], s[24:25], v93, s77, v[122:123]
	v_cvt_pk_bf16_f32 v90, v90, v91
	v_cvt_pk_bf16_f32 v91, v100, v101
	v_lshl_add_u64 v[94:95], v[94:95], 0, v[124:125]
	global_store_dwordx4 v[94:95], v[88:91], off sc1
	s_nop 1
	v_pk_mul_f32 v[84:85], v[84:85], v[92:93] op_sel_hi:[1,0]
	v_pk_mul_f32 v[88:89], v[78:79], v[92:93] op_sel_hi:[1,0]
	v_pk_mul_f32 v[78:79], v[76:77], v[92:93] op_sel_hi:[1,0]
	v_pk_mul_f32 v[86:87], v[86:87], v[92:93] op_sel_hi:[1,0]
	v_cvt_pk_bf16_f32 v76, v84, v85
	v_lshl_add_u64 v[84:85], v[94:95], 0, s[66:67]
	v_cvt_pk_bf16_f32 v77, v86, v87
	v_cvt_pk_bf16_f32 v78, v78, v79
	v_cvt_pk_bf16_f32 v79, v88, v89
	s_nop 0
	global_store_dwordx4 v[84:85], v[76:79], off sc1
	s_nop 1
	v_mov_b32_e32 v76, v226
	v_or_b32_e32 v77, 48, v149
	s_waitcnt lgkmcnt(0)
	v_pk_mul_f32 v[78:79], v[82:83], v[76:77] op_sel_hi:[1,0]
	v_pk_mul_f32 v[80:81], v[80:81], v[76:77] op_sel_hi:[1,0]
	v_pk_mul_f32 v[82:83], v[74:75], v[76:77] op_sel_hi:[1,0]
	v_pk_mul_f32 v[74:75], v[72:73], v[76:77] op_sel_hi:[1,0]
	v_cvt_pk_bf16_f32 v72, v80, v81
	v_cvt_pk_bf16_f32 v73, v78, v79
	v_mad_i64_i32 v[78:79], s[24:25], v77, s77, v[122:123]
	v_cvt_pk_bf16_f32 v74, v74, v75
	v_cvt_pk_bf16_f32 v75, v82, v83
	v_lshl_add_u64 v[78:79], v[78:79], 0, v[124:125]
	global_store_dwordx4 v[78:79], v[72:75], off sc1
	s_nop 1
	v_pk_mul_f32 v[68:69], v[68:69], v[76:77] op_sel_hi:[1,0]
	v_pk_mul_f32 v[72:73], v[66:67], v[76:77] op_sel_hi:[1,0]
	v_pk_mul_f32 v[66:67], v[64:65], v[76:77] op_sel_hi:[1,0]
	v_pk_mul_f32 v[70:71], v[70:71], v[76:77] op_sel_hi:[1,0]
	v_cvt_pk_bf16_f32 v64, v68, v69
	v_lshl_add_u64 v[68:69], v[78:79], 0, s[66:67]
	v_cvt_pk_bf16_f32 v65, v70, v71
	v_cvt_pk_bf16_f32 v66, v66, v67
	v_cvt_pk_bf16_f32 v67, v72, v73
	s_nop 0
	global_store_dwordx4 v[68:69], v[64:67], off sc1
	s_nop 1
	v_mov_b32_e32 v64, v227
	v_add_u32_e32 v65, 0x80, v149
	s_waitcnt lgkmcnt(0)
	v_pk_mul_f32 v[60:61], v[60:61], v[64:65] op_sel_hi:[1,0]
	v_pk_mul_f32 v[62:63], v[62:63], v[64:65] op_sel_hi:[1,0]
	v_pk_mul_f32 v[66:67], v[58:59], v[64:65] op_sel_hi:[1,0]
	v_pk_mul_f32 v[58:59], v[56:57], v[64:65] op_sel_hi:[1,0]
	v_cvt_pk_bf16_f32 v56, v60, v61
	v_cvt_pk_bf16_f32 v57, v62, v63
	v_mad_i64_i32 v[60:61], s[24:25], v65, s77, v[122:123]
	v_cvt_pk_bf16_f32 v58, v58, v59
	v_cvt_pk_bf16_f32 v59, v66, v67
	v_lshl_add_u64 v[60:61], v[60:61], 0, v[124:125]
	global_store_dwordx4 v[60:61], v[56:59], off sc1
	s_nop 1
	v_pk_mul_f32 v[52:53], v[52:53], v[64:65] op_sel_hi:[1,0]
	v_pk_mul_f32 v[56:57], v[46:47], v[64:65] op_sel_hi:[1,0]
	v_pk_mul_f32 v[46:47], v[44:45], v[64:65] op_sel_hi:[1,0]
	v_pk_mul_f32 v[54:55], v[54:55], v[64:65] op_sel_hi:[1,0]
	v_cvt_pk_bf16_f32 v44, v52, v53
	v_lshl_add_u64 v[52:53], v[60:61], 0, s[66:67]
	v_cvt_pk_bf16_f32 v45, v54, v55
	v_cvt_pk_bf16_f32 v46, v46, v47
	v_cvt_pk_bf16_f32 v47, v56, v57
	s_nop 0
	global_store_dwordx4 v[52:53], v[44:47], off sc1
	s_nop 1
	v_mov_b32_e32 v44, v228
	v_add_u32_e32 v45, 0x90, v149
	s_waitcnt lgkmcnt(0)
	v_pk_mul_f32 v[46:47], v[50:51], v[44:45] op_sel_hi:[1,0]
	v_pk_mul_f32 v[48:49], v[48:49], v[44:45] op_sel_hi:[1,0]
	v_pk_mul_f32 v[50:51], v[42:43], v[44:45] op_sel_hi:[1,0]
	v_pk_mul_f32 v[42:43], v[40:41], v[44:45] op_sel_hi:[1,0]
	v_cvt_pk_bf16_f32 v40, v48, v49
	v_cvt_pk_bf16_f32 v41, v46, v47
	v_mad_i64_i32 v[46:47], s[24:25], v45, s77, v[122:123]
	v_cvt_pk_bf16_f32 v42, v42, v43
	v_cvt_pk_bf16_f32 v43, v50, v51
	v_lshl_add_u64 v[46:47], v[46:47], 0, v[124:125]
	global_store_dwordx4 v[46:47], v[40:43], off sc1
	s_nop 1
	v_pk_mul_f32 v[36:37], v[36:37], v[44:45] op_sel_hi:[1,0]
	v_pk_mul_f32 v[40:41], v[30:31], v[44:45] op_sel_hi:[1,0]
	v_pk_mul_f32 v[30:31], v[28:29], v[44:45] op_sel_hi:[1,0]
	v_pk_mul_f32 v[38:39], v[38:39], v[44:45] op_sel_hi:[1,0]
	v_cvt_pk_bf16_f32 v28, v36, v37
	v_lshl_add_u64 v[36:37], v[46:47], 0, s[66:67]
	v_cvt_pk_bf16_f32 v29, v38, v39
	v_cvt_pk_bf16_f32 v30, v30, v31
	v_cvt_pk_bf16_f32 v31, v40, v41
	s_nop 0
	global_store_dwordx4 v[36:37], v[28:31], off sc1
	s_nop 1
	v_mov_b32_e32 v28, v229
	v_add_u32_e32 v29, 0xa0, v149
	s_waitcnt lgkmcnt(0)
	v_pk_mul_f32 v[30:31], v[34:35], v[28:29] op_sel_hi:[1,0]
	v_pk_mul_f32 v[32:33], v[32:33], v[28:29] op_sel_hi:[1,0]
	v_pk_mul_f32 v[34:35], v[26:27], v[28:29] op_sel_hi:[1,0]
	v_pk_mul_f32 v[26:27], v[24:25], v[28:29] op_sel_hi:[1,0]
	v_cvt_pk_bf16_f32 v24, v32, v33
	v_cvt_pk_bf16_f32 v25, v30, v31
	v_mad_i64_i32 v[30:31], s[24:25], v29, s77, v[122:123]
	v_cvt_pk_bf16_f32 v26, v26, v27
	v_cvt_pk_bf16_f32 v27, v34, v35
	v_lshl_add_u64 v[30:31], v[30:31], 0, v[124:125]
	global_store_dwordx4 v[30:31], v[24:27], off sc1
	s_nop 1
	v_pk_mul_f32 v[20:21], v[20:21], v[28:29] op_sel_hi:[1,0]
	v_pk_mul_f32 v[24:25], v[14:15], v[28:29] op_sel_hi:[1,0]
	v_pk_mul_f32 v[14:15], v[12:13], v[28:29] op_sel_hi:[1,0]
	v_pk_mul_f32 v[22:23], v[22:23], v[28:29] op_sel_hi:[1,0]
	v_cvt_pk_bf16_f32 v12, v20, v21
	v_lshl_add_u64 v[20:21], v[30:31], 0, s[66:67]
	v_cvt_pk_bf16_f32 v13, v22, v23
	v_cvt_pk_bf16_f32 v14, v14, v15
	v_cvt_pk_bf16_f32 v15, v24, v25
	s_nop 0
	global_store_dwordx4 v[20:21], v[12:15], off sc1
	s_nop 1
	v_mov_b32_e32 v12, v230
	v_add_u32_e32 v13, 0xb0, v149
	s_waitcnt lgkmcnt(0)
	v_pk_mul_f32 v[14:15], v[18:19], v[12:13] op_sel_hi:[1,0]
	v_pk_mul_f32 v[16:17], v[16:17], v[12:13] op_sel_hi:[1,0]
	v_pk_mul_f32 v[18:19], v[10:11], v[12:13] op_sel_hi:[1,0]
	v_pk_mul_f32 v[10:11], v[8:9], v[12:13] op_sel_hi:[1,0]
	v_cvt_pk_bf16_f32 v8, v16, v17
	v_cvt_pk_bf16_f32 v9, v14, v15
	v_mad_i64_i32 v[14:15], s[24:25], v13, s77, v[122:123]
	v_cvt_pk_bf16_f32 v10, v10, v11
	v_cvt_pk_bf16_f32 v11, v18, v19
	v_lshl_add_u64 v[14:15], v[14:15], 0, v[124:125]
	global_store_dwordx4 v[14:15], v[8:11], off sc1
	s_nop 1
	v_pk_mul_f32 v[4:5], v[4:5], v[12:13] op_sel_hi:[1,0]
	v_pk_mul_f32 v[8:9], v[2:3], v[12:13] op_sel_hi:[1,0]
	v_pk_mul_f32 v[2:3], v[0:1], v[12:13] op_sel_hi:[1,0]
	v_pk_mul_f32 v[6:7], v[6:7], v[12:13] op_sel_hi:[1,0]
	v_cvt_pk_bf16_f32 v0, v4, v5
	v_lshl_add_u64 v[4:5], v[14:15], 0, s[66:67]
	v_cvt_pk_bf16_f32 v1, v6, v7
	v_cvt_pk_bf16_f32 v2, v2, v3
	v_cvt_pk_bf16_f32 v3, v8, v9
	s_nop 0
	global_store_dwordx4 v[4:5], v[0:3], off sc1
	s_nop 1
	s_cbranch_vccnz .LBB0_718
	s_andn2_b64 vcc, exec, s[6:7]
	s_cbranch_vccnz .LBB0_717
	s_barrier
	s_branch .LBB0_717
